# all changes together: conversion gain hoist, GLA pre-pass and attention wait fixes, aligned MFMA runs, XCD-split last FFN-up round with 4 idle tiles, flat barrier release
# baseline (speedup 1.0000x reference)
; #define PG8_WAIT_V(n) asm volatile("s_waitcnt vmcnt(" #n ")" ::: "memory")
; #define PG8_WAIT_L(n) asm volatile("s_waitcnt lgkmcnt(" #n ")" ::: "memory")
; #define PG8_BAR __builtin_amdgcn_s_barrier()
; #define PG8_SCHED __builtin_amdgcn_sched_barrier(0)
; template <class Epi, class Sched, bool ALIGN_EPI = false, bool SP2 = false, bool F8 = false>
; __device__ __forceinline__ void gemm_phase(PG8_LAS unsigned char* lds, const Gemm g, const Sched& S, const Epi& E) {
;     ...
;         for (int t = 0; t < nt; t += 2) {
;             const bool last = (t == nt - 2);
;             const char* a1 = cA + (size_t)(t + 1) * kstep;
;             const char* a2 = last ? nA : cA + (size_t)(t + 2) * kstep; const char* b2 = last ? nB : cB + (size_t)(t + 2) * kstep;
;             const char* a3 = a2 + kstep; const char* b3 = b2 + kstep;
;             if (last && has_next) S.a_ready(nxt);
;             if constexpr (SP2) {
;             PG8_LDB(B0, 0, 0); PG8_LDB(B1, 0, 1); PG8_SCHED; PG8_LDA(At, 0, 0); PG8_STAGE(PG8_SA(1, 1), a1 + hstep, voffA);
;             PG8_WAIT_V(8); PG8_WAIT_L(0); PG8_BAR; PG8_MMA(0, 0, At, B0); PG8_MMA(0, 1, At, B1); PG8_BAR; PG8_SCHED;
;             PG8_LDA(At, 0, 1); PG8_STAGE(PG8_SB(0, 0), b2, voffB); PG8_STAGE(PG8_SB(0, 1), b2 + hstep, voffB); PG8_STAGE(PG8_SA(0, 0), a2, voffA);
;             PG8_WAIT_V(8); PG8_WAIT_L(0); PG8_BAR; PG8_MMA(1, 0, At, B0); PG8_MMA(1, 1, At, B1); PG8_BAR; PG8_SCHED;
.LBB0_297:
	s_add_u32 s18, s16, 0x4000
	s_addc_u32 s19, s17, 0
	s_cmp_eq_u32 s63, 28
	s_cselect_b32 s30, s59, s18
	s_cselect_b32 s31, s11, s19
	s_cselect_b32 s22, s60, s61
	s_cselect_b32 s23, s9, s62
	s_add_u32 s20, s30, 0x2000
	s_addc_u32 s21, s31, 0
	s_add_i32 s65, 0, 0x10000
	v_add_u32_e32 v145, s65, v153
	s_add_i32 s67, 0, 0x14000
	ds_read_b128 v[156:159], v145
	ds_read_b128 v[160:163], v145 offset:1024
	ds_read_b128 v[164:167], v145 offset:2048
	ds_read_b128 v[168:171], v145 offset:3072
	v_add_u32_e32 v145, s67, v153
	ds_read_b128 v[184:187], v145
	ds_read_b128 v[188:191], v145 offset:1024
	ds_read_b128 v[192:195], v145 offset:2048
	ds_read_b128 v[196:199], v145 offset:3072
	s_add_u32 s46, s16, 0x2000
	s_addc_u32 s47, s17, 0
	s_mov_b32 m0, s50
	ds_read_b128 v[200:203], v155
	ds_read_b128 v[204:207], v155 offset:1024
	ds_read_b128 v[208:211], v155 offset:2048
	ds_read_b128 v[228:231], v155 offset:3072
	ds_read_b128 v[232:235], v155 offset:4096
	ds_read_b128 v[236:239], v155 offset:5120
	ds_read_b128 v[240:243], v155 offset:6144
	ds_read_b128 v[244:247], v155 offset:7168
	global_load_lds_dwordx4 v138, s[46:47]
	s_mov_b32 m0, s52
	s_nop 0
	global_load_lds_dwordx4 v134, s[46:47]
	s_add_i32 m0, s40, 0xc000
	s_nop 0
	global_load_lds_dwordx4 v140, s[16:17]
	s_add_i32 m0, s40, 0xe000
	s_nop 0
	global_load_lds_dwordx4 v142, s[16:17]
	s_waitcnt vmcnt(8)
	s_waitcnt lgkmcnt(0)
	s_nop 0
	s_nop 0
	s_barrier
	s_setprio 1
	s_waitcnt lgkmcnt(0)
	v_mfma_f32_16x16x32_bf16 v[128:131], v[156:159], v[200:203], v[128:131]
	v_mfma_f32_16x16x32_bf16 v[124:127], v[164:167], v[200:203], v[124:127]
	v_mfma_f32_16x16x32_bf16 v[112:115], v[156:159], v[208:211], v[112:115]
	v_mfma_f32_16x16x32_bf16 v[108:111], v[164:167], v[208:211], v[108:111]
	v_mfma_f32_16x16x32_bf16 v[96:99], v[156:159], v[232:235], v[96:99]
	v_mfma_f32_16x16x32_bf16 v[92:95], v[164:167], v[232:235], v[92:95]
	v_mfma_f32_16x16x32_bf16 v[80:83], v[156:159], v[240:243], v[80:83]
	v_mfma_f32_16x16x32_bf16 v[76:79], v[164:167], v[240:243], v[76:79]
	v_mfma_f32_16x16x32_bf16 v[128:131], v[160:163], v[204:207], v[128:131]
	v_mfma_f32_16x16x32_bf16 v[124:127], v[168:171], v[204:207], v[124:127]
	v_mfma_f32_16x16x32_bf16 v[112:115], v[160:163], v[228:231], v[112:115]
	v_mfma_f32_16x16x32_bf16 v[108:111], v[168:171], v[228:231], v[108:111]
	v_mfma_f32_16x16x32_bf16 v[96:99], v[160:163], v[236:239], v[96:99]
	v_mfma_f32_16x16x32_bf16 v[92:95], v[168:171], v[236:239], v[92:95]
	v_mfma_f32_16x16x32_bf16 v[80:83], v[160:163], v[244:247], v[80:83]
	v_mfma_f32_16x16x32_bf16 v[76:79], v[168:171], v[244:247], v[76:79]
	s_setprio 0
	s_setprio 1
	v_mfma_f32_16x16x32_bf16 v[120:123], v[184:187], v[200:203], v[120:123]
	v_mfma_f32_16x16x32_bf16 v[116:119], v[192:195], v[200:203], v[116:119]
	v_mfma_f32_16x16x32_bf16 v[104:107], v[184:187], v[208:211], v[104:107]
	v_mfma_f32_16x16x32_bf16 v[100:103], v[192:195], v[208:211], v[100:103]
	v_mfma_f32_16x16x32_bf16 v[88:91], v[184:187], v[232:235], v[88:91]
	v_mfma_f32_16x16x32_bf16 v[84:87], v[192:195], v[232:235], v[84:87]
	v_mfma_f32_16x16x32_bf16 v[72:75], v[184:187], v[240:243], v[72:75]
	v_mfma_f32_16x16x32_bf16 v[68:71], v[192:195], v[240:243], v[68:71]
	v_mfma_f32_16x16x32_bf16 v[120:123], v[188:191], v[204:207], v[120:123]
	v_mfma_f32_16x16x32_bf16 v[116:119], v[196:199], v[204:207], v[116:119]
	v_mfma_f32_16x16x32_bf16 v[104:107], v[188:191], v[228:231], v[104:107]
	v_mfma_f32_16x16x32_bf16 v[100:103], v[196:199], v[228:231], v[100:103]
	v_mfma_f32_16x16x32_bf16 v[88:91], v[188:191], v[236:239], v[88:91]
	v_mfma_f32_16x16x32_bf16 v[84:87], v[196:199], v[236:239], v[84:87]
	v_mfma_f32_16x16x32_bf16 v[72:75], v[188:191], v[244:247], v[72:75]
	v_mfma_f32_16x16x32_bf16 v[68:71], v[196:199], v[244:247], v[68:71]
	s_setprio 0
	s_barrier
	s_add_i32 s16, s65, s26
	s_mov_b32 m0, s16
	ds_read_b128 v[200:203], v155 offset:16384
	ds_read_b128 v[204:207], v155 offset:17408
	ds_read_b128 v[208:211], v155 offset:18432
	ds_read_b128 v[228:231], v155 offset:19456
	ds_read_b128 v[232:235], v155 offset:20480
	ds_read_b128 v[236:239], v155 offset:21504
	ds_read_b128 v[240:243], v155 offset:22528
	ds_read_b128 v[244:247], v155 offset:23552
	global_load_lds_dwordx4 v136, s[22:23]
	s_add_i32 m0, s16, 0x2000
	s_add_u32 s16, s22, 0x80000
	s_addc_u32 s17, s23, 0
	s_add_i32 s65, s67, s26
	global_load_lds_dwordx4 v132, s[22:23]
	s_mov_b32 m0, s65
	s_nop 0
	global_load_lds_dwordx4 v136, s[16:17]
	s_add_i32 m0, s65, 0x2000
	s_nop 0
	global_load_lds_dwordx4 v132, s[16:17]
	s_waitcnt vmcnt(6)
	s_waitcnt lgkmcnt(0)
	s_barrier
; #define PG8_WAIT_V(n) asm volatile("s_waitcnt vmcnt(" #n ")" ::: "memory")
; #define PG8_WAIT_L(n) asm volatile("s_waitcnt lgkmcnt(" #n ")" ::: "memory")
; #define PG8_BAR __builtin_amdgcn_s_barrier()
; #define PG8_SCHED __builtin_amdgcn_sched_barrier(0)
; template <class Epi, class Sched, bool ALIGN_EPI = false, bool SP2 = false, bool F8 = false>
; __device__ __forceinline__ void gemm_phase(PG8_LAS unsigned char* lds, const Gemm g, const Sched& S, const Epi& E) {
;     ...
;             PG8_WAIT_V(8); PG8_WAIT_L(0); PG8_BAR; PG8_MMA(1, 0, At, B0); PG8_MMA(1, 1, At, B1); PG8_BAR; PG8_SCHED;
;             PG8_LDB(B0, 1, 0); PG8_LDB(B1, 1, 1); PG8_SCHED; PG8_LDA(At, 1, 0); PG8_STAGE(PG8_SA(0, 1), a2 + hstep, voffA);
;             PG8_WAIT_V(8); PG8_WAIT_L(0); PG8_BAR; PG8_MMA(0, 0, At, B0); PG8_MMA(0, 1, At, B1); PG8_BAR; PG8_SCHED;
	s_setprio 1
	s_waitcnt lgkmcnt(0)
	v_mfma_f32_16x16x32_bf16 v[64:67], v[156:159], v[200:203], v[64:67]
	v_mfma_f32_16x16x32_bf16 v[60:63], v[164:167], v[200:203], v[60:63]
	v_mfma_f32_16x16x32_bf16 v[48:51], v[156:159], v[208:211], v[48:51]
	v_mfma_f32_16x16x32_bf16 v[44:47], v[164:167], v[208:211], v[44:47]
	v_mfma_f32_16x16x32_bf16 v[32:35], v[156:159], v[232:235], v[32:35]
	v_mfma_f32_16x16x32_bf16 v[28:31], v[164:167], v[232:235], v[28:31]
	v_mfma_f32_16x16x32_bf16 v[16:19], v[156:159], v[240:243], v[16:19]
	v_mfma_f32_16x16x32_bf16 v[12:15], v[164:167], v[240:243], v[12:15]
	v_mfma_f32_16x16x32_bf16 v[64:67], v[160:163], v[204:207], v[64:67]
	v_mfma_f32_16x16x32_bf16 v[60:63], v[168:171], v[204:207], v[60:63]
	v_mfma_f32_16x16x32_bf16 v[48:51], v[160:163], v[228:231], v[48:51]
	v_mfma_f32_16x16x32_bf16 v[44:47], v[168:171], v[228:231], v[44:47]
	v_mfma_f32_16x16x32_bf16 v[32:35], v[160:163], v[236:239], v[32:35]
	v_mfma_f32_16x16x32_bf16 v[28:31], v[168:171], v[236:239], v[28:31]
	v_mfma_f32_16x16x32_bf16 v[16:19], v[160:163], v[244:247], v[16:19]
	v_mfma_f32_16x16x32_bf16 v[12:15], v[168:171], v[244:247], v[12:15]
	s_setprio 0
	s_setprio 1
	v_mfma_f32_16x16x32_bf16 v[56:59], v[184:187], v[200:203], v[56:59]
	v_mfma_f32_16x16x32_bf16 v[52:55], v[192:195], v[200:203], v[52:55]
	v_mfma_f32_16x16x32_bf16 v[40:43], v[184:187], v[208:211], v[40:43]
	v_mfma_f32_16x16x32_bf16 v[36:39], v[192:195], v[208:211], v[36:39]
	v_mfma_f32_16x16x32_bf16 v[24:27], v[184:187], v[232:235], v[24:27]
	v_mfma_f32_16x16x32_bf16 v[20:23], v[192:195], v[232:235], v[20:23]
	v_mfma_f32_16x16x32_bf16 v[8:11], v[184:187], v[240:243], v[8:11]
	v_mfma_f32_16x16x32_bf16 v[4:7], v[192:195], v[240:243], v[4:7]
	v_mfma_f32_16x16x32_bf16 v[56:59], v[188:191], v[204:207], v[56:59]
	v_mfma_f32_16x16x32_bf16 v[52:55], v[196:199], v[204:207], v[52:55]
	v_mfma_f32_16x16x32_bf16 v[40:43], v[188:191], v[228:231], v[40:43]
	v_mfma_f32_16x16x32_bf16 v[36:39], v[196:199], v[228:231], v[36:39]
	v_mfma_f32_16x16x32_bf16 v[24:27], v[188:191], v[236:239], v[24:27]
	v_mfma_f32_16x16x32_bf16 v[20:23], v[196:199], v[236:239], v[20:23]
	v_mfma_f32_16x16x32_bf16 v[8:11], v[188:191], v[244:247], v[8:11]
	v_mfma_f32_16x16x32_bf16 v[4:7], v[196:199], v[244:247], v[4:7]
	s_setprio 0
	s_barrier
	s_add_i32 s65, 0, 0x18000
	v_add_u32_e32 v145, s65, v153
	s_add_i32 s67, 0, 0x1c000
	ds_read_b128 v[156:159], v145
	ds_read_b128 v[160:163], v145 offset:1024
	ds_read_b128 v[164:167], v145 offset:2048
	ds_read_b128 v[168:171], v145 offset:3072
	v_add_u32_e32 v145, s67, v153
	ds_read_b128 v[184:187], v145
	ds_read_b128 v[188:191], v145 offset:1024
	ds_read_b128 v[192:195], v145 offset:2048
	ds_read_b128 v[196:199], v145 offset:3072
	s_add_u32 s16, s30, 0x80000
	s_addc_u32 s17, s31, 0
	s_mov_b32 m0, s40
	ds_read_b128 v[200:203], v155 offset:32768
	ds_read_b128 v[204:207], v155 offset:33792
	ds_read_b128 v[208:211], v155 offset:34816
	ds_read_b128 v[228:231], v155 offset:35840
	ds_read_b128 v[232:235], v155 offset:36864
	ds_read_b128 v[236:239], v155 offset:37888
	ds_read_b128 v[240:243], v155 offset:38912
	ds_read_b128 v[244:247], v155 offset:39936
	global_load_lds_dwordx4 v138, s[30:31]
	s_mov_b32 m0, s41
	s_nop 0
	global_load_lds_dwordx4 v134, s[30:31]
	s_mov_b32 m0, s42
	s_nop 0
	global_load_lds_dwordx4 v138, s[16:17]
	s_mov_b32 m0, s45
	s_nop 0
	global_load_lds_dwordx4 v134, s[16:17]
	s_waitcnt vmcnt(8)
	s_waitcnt lgkmcnt(0)
	s_nop 0
	s_barrier
; #define PG8_WAIT_V(n) asm volatile("s_waitcnt vmcnt(" #n ")" ::: "memory")
; #define PG8_WAIT_L(n) asm volatile("s_waitcnt lgkmcnt(" #n ")" ::: "memory")
; #define PG8_BAR __builtin_amdgcn_s_barrier()
; #define PG8_SCHED __builtin_amdgcn_sched_barrier(0)
; template <class Epi, class Sched, bool ALIGN_EPI = false, bool SP2 = false, bool F8 = false>
; __device__ __forceinline__ void gemm_phase(PG8_LAS unsigned char* lds, const Gemm g, const Sched& S, const Epi& E) {
;     ...
;         for (int t = 0; t < nt; t += 2) {
;     ...
;             PG8_WAIT_V(8); PG8_WAIT_L(0); PG8_BAR; PG8_MMA(0, 0, At, B0); PG8_MMA(0, 1, At, B1); PG8_BAR; PG8_SCHED;
;             PG8_LDA(At, 1, 1); PG8_STAGE(PG8_SB(1, 0), b3, voffB); PG8_STAGE(PG8_SB(1, 1), b3 + hstep, voffB); PG8_STAGE(PG8_SA(1, 0), a3, voffA);
;             PG8_WAIT_V(8); PG8_WAIT_L(0); PG8_BAR; PG8_MMA(1, 0, At, B0); PG8_MMA(1, 1, At, B1); PG8_BAR; PG8_SCHED;
	s_setprio 1
	s_waitcnt lgkmcnt(0)
	v_mfma_f32_16x16x32_bf16 v[128:131], v[156:159], v[200:203], v[128:131]
	v_mfma_f32_16x16x32_bf16 v[124:127], v[164:167], v[200:203], v[124:127]
	v_mfma_f32_16x16x32_bf16 v[112:115], v[156:159], v[208:211], v[112:115]
	v_mfma_f32_16x16x32_bf16 v[108:111], v[164:167], v[208:211], v[108:111]
	v_mfma_f32_16x16x32_bf16 v[96:99], v[156:159], v[232:235], v[96:99]
	v_mfma_f32_16x16x32_bf16 v[92:95], v[164:167], v[232:235], v[92:95]
	v_mfma_f32_16x16x32_bf16 v[80:83], v[156:159], v[240:243], v[80:83]
	v_mfma_f32_16x16x32_bf16 v[76:79], v[164:167], v[240:243], v[76:79]
	v_mfma_f32_16x16x32_bf16 v[128:131], v[160:163], v[204:207], v[128:131]
	v_mfma_f32_16x16x32_bf16 v[124:127], v[168:171], v[204:207], v[124:127]
	v_mfma_f32_16x16x32_bf16 v[112:115], v[160:163], v[228:231], v[112:115]
	v_mfma_f32_16x16x32_bf16 v[108:111], v[168:171], v[228:231], v[108:111]
	v_mfma_f32_16x16x32_bf16 v[96:99], v[160:163], v[236:239], v[96:99]
	v_mfma_f32_16x16x32_bf16 v[92:95], v[168:171], v[236:239], v[92:95]
	v_mfma_f32_16x16x32_bf16 v[80:83], v[160:163], v[244:247], v[80:83]
	v_mfma_f32_16x16x32_bf16 v[76:79], v[168:171], v[244:247], v[76:79]
	s_setprio 0
	s_setprio 1
	v_mfma_f32_16x16x32_bf16 v[120:123], v[184:187], v[200:203], v[120:123]
	v_mfma_f32_16x16x32_bf16 v[116:119], v[192:195], v[200:203], v[116:119]
	v_mfma_f32_16x16x32_bf16 v[104:107], v[184:187], v[208:211], v[104:107]
	v_mfma_f32_16x16x32_bf16 v[100:103], v[192:195], v[208:211], v[100:103]
	v_mfma_f32_16x16x32_bf16 v[88:91], v[184:187], v[232:235], v[88:91]
	v_mfma_f32_16x16x32_bf16 v[84:87], v[192:195], v[232:235], v[84:87]
	v_mfma_f32_16x16x32_bf16 v[72:75], v[184:187], v[240:243], v[72:75]
	v_mfma_f32_16x16x32_bf16 v[68:71], v[192:195], v[240:243], v[68:71]
	v_mfma_f32_16x16x32_bf16 v[120:123], v[188:191], v[204:207], v[120:123]
	v_mfma_f32_16x16x32_bf16 v[116:119], v[196:199], v[204:207], v[116:119]
	v_mfma_f32_16x16x32_bf16 v[104:107], v[188:191], v[228:231], v[104:107]
	v_mfma_f32_16x16x32_bf16 v[100:103], v[196:199], v[228:231], v[100:103]
	v_mfma_f32_16x16x32_bf16 v[88:91], v[188:191], v[236:239], v[88:91]
	v_mfma_f32_16x16x32_bf16 v[84:87], v[196:199], v[236:239], v[84:87]
	v_mfma_f32_16x16x32_bf16 v[72:75], v[188:191], v[244:247], v[72:75]
	v_mfma_f32_16x16x32_bf16 v[68:71], v[196:199], v[244:247], v[68:71]
	s_setprio 0
	s_barrier
	s_add_u32 s16, s22, 0x2000
	s_addc_u32 s17, s23, 0
	s_add_i32 s30, s65, s26
	s_mov_b32 m0, s30
	ds_read_b128 v[200:203], v155 offset:49152
	ds_read_b128 v[204:207], v155 offset:50176
	ds_read_b128 v[208:211], v155 offset:51200
	ds_read_b128 v[228:231], v155 offset:52224
	ds_read_b128 v[232:235], v155 offset:53248
	ds_read_b128 v[236:239], v155 offset:54272
	ds_read_b128 v[240:243], v155 offset:55296
	ds_read_b128 v[244:247], v155 offset:56320
	global_load_lds_dwordx4 v136, s[16:17]
	s_add_i32 m0, s30, 0x2000
	s_nop 0
	global_load_lds_dwordx4 v132, s[16:17]
	s_add_u32 s16, s22, 0x82000
	s_addc_u32 s17, s23, 0
	s_add_i32 s22, s67, s26
	s_mov_b32 m0, s22
	s_nop 0
	global_load_lds_dwordx4 v136, s[16:17]
	s_add_i32 m0, s22, 0x2000
	s_nop 0
	global_load_lds_dwordx4 v132, s[16:17]
	s_waitcnt vmcnt(6)
	s_waitcnt lgkmcnt(0)
	s_barrier
	s_setprio 1
	s_waitcnt lgkmcnt(0)
	v_mfma_f32_16x16x32_bf16 v[64:67], v[156:159], v[200:203], v[64:67]
	v_mfma_f32_16x16x32_bf16 v[60:63], v[164:167], v[200:203], v[60:63]
	v_mfma_f32_16x16x32_bf16 v[48:51], v[156:159], v[208:211], v[48:51]
	v_mfma_f32_16x16x32_bf16 v[44:47], v[164:167], v[208:211], v[44:47]
	v_mfma_f32_16x16x32_bf16 v[32:35], v[156:159], v[232:235], v[32:35]
	v_mfma_f32_16x16x32_bf16 v[28:31], v[164:167], v[232:235], v[28:31]
	v_mfma_f32_16x16x32_bf16 v[16:19], v[156:159], v[240:243], v[16:19]
	v_mfma_f32_16x16x32_bf16 v[12:15], v[164:167], v[240:243], v[12:15]
	v_mfma_f32_16x16x32_bf16 v[64:67], v[160:163], v[204:207], v[64:67]
	v_mfma_f32_16x16x32_bf16 v[60:63], v[168:171], v[204:207], v[60:63]
	v_mfma_f32_16x16x32_bf16 v[48:51], v[160:163], v[228:231], v[48:51]
	v_mfma_f32_16x16x32_bf16 v[44:47], v[168:171], v[228:231], v[44:47]
	v_mfma_f32_16x16x32_bf16 v[32:35], v[160:163], v[236:239], v[32:35]
	v_mfma_f32_16x16x32_bf16 v[28:31], v[168:171], v[236:239], v[28:31]
	v_mfma_f32_16x16x32_bf16 v[16:19], v[160:163], v[244:247], v[16:19]
	v_mfma_f32_16x16x32_bf16 v[12:15], v[168:171], v[244:247], v[12:15]
	s_setprio 0
	s_setprio 1
	v_mfma_f32_16x16x32_bf16 v[56:59], v[184:187], v[200:203], v[56:59]
	v_mfma_f32_16x16x32_bf16 v[52:55], v[192:195], v[200:203], v[52:55]
	v_mfma_f32_16x16x32_bf16 v[40:43], v[184:187], v[208:211], v[40:43]
	v_mfma_f32_16x16x32_bf16 v[36:39], v[192:195], v[208:211], v[36:39]
	v_mfma_f32_16x16x32_bf16 v[24:27], v[184:187], v[232:235], v[24:27]
	v_mfma_f32_16x16x32_bf16 v[20:23], v[192:195], v[232:235], v[20:23]
	v_mfma_f32_16x16x32_bf16 v[8:11], v[184:187], v[240:243], v[8:11]
	v_mfma_f32_16x16x32_bf16 v[4:7], v[192:195], v[240:243], v[4:7]
	v_mfma_f32_16x16x32_bf16 v[56:59], v[188:191], v[204:207], v[56:59]
	v_mfma_f32_16x16x32_bf16 v[52:55], v[196:199], v[204:207], v[52:55]
	v_mfma_f32_16x16x32_bf16 v[40:43], v[188:191], v[228:231], v[40:43]
	v_mfma_f32_16x16x32_bf16 v[36:39], v[196:199], v[228:231], v[36:39]
	v_mfma_f32_16x16x32_bf16 v[24:27], v[188:191], v[236:239], v[24:27]
	v_mfma_f32_16x16x32_bf16 v[20:23], v[196:199], v[236:239], v[20:23]
	v_mfma_f32_16x16x32_bf16 v[8:11], v[188:191], v[244:247], v[8:11]
	v_mfma_f32_16x16x32_bf16 v[4:7], v[196:199], v[244:247], v[4:7]
	s_setprio 0
	s_barrier
	s_add_i32 s63, s63, 2
	s_add_u32 s61, s61, 0x4000
	s_addc_u32 s62, s62, 0
	s_cmp_gt_u32 s63, 29
	s_mov_b64 s[16:17], s[18:19]
	s_cbranch_scc0 .LBB0_297
	s_and_b64 vcc, exec, s[6:7]
	s_cbranch_vccz .LBB0_300
	s_barrier
